# attention prologue: shift, bias rows and key gains fetched together with one wait; modulate row reduction via DPP and permlane swaps
# baseline (speedup 1.0000x reference)
.LBB0_189:
	v_cndmask_b32_e64 v0, 0, 1, s[0:1]
	v_readlane_b32 s4, v252, 57
	s_andn2_b64 vcc, exec, s[0:1]
	s_and_b32 s18, s3, 7
	s_lshl_b32 s100, s18, 7
	s_add_u32 s100, s92, s100
	s_addc_u32 s101, s93, 0
	v_lshlrev_b32_e32 v100, 3, v175
	v_and_b32_e32 v100, 56, v100
	v_lshlrev_b32_e32 v100, 1, v100
	v_ashrrev_i32_e32 v101, 3, v175
	v_add_u32_e32 v101, s11, v101
	v_mul_u32_u24_e32 v101, 0x1200, v101
	v_add_u32_e32 v101, v101, v100
	global_load_dwordx4 v[104:107], v101, s[100:101]
	v_add_u32_e32 v101, 0x24000, v101
	global_load_dwordx4 v[108:111], v101, s[100:101]
	v_add_u32_e32 v101, 0x24000, v101
	global_load_dwordx4 v[112:115], v101, s[100:101]
	v_add_u32_e32 v101, 0x24000, v101
	global_load_dwordx4 v[116:119], v101, s[100:101]
	v_add_u32_e32 v101, 0x24000, v101
	global_load_dwordx4 v[120:123], v101, s[100:101]
	v_add_u32_e32 v101, 0x24000, v101
	global_load_dwordx4 v[124:127], v101, s[100:101]
	v_add_u32_e32 v101, 0x24000, v101
	global_load_dwordx4 v[128:131], v101, s[100:101]
	v_add_u32_e32 v101, 0x24000, v101
	global_load_dwordx4 v[132:135], v101, s[100:101]
	s_lshl_b32 s100, s15, 11
	s_lshl_b32 s101, s14, 6
	s_or_b32 s100, s100, s101
	s_lshl_b32 s101, s15, 8
	s_addk_i32 s101, 0x4000
	s_lshl_b32 s26, s13, 6
	s_sub_i32 s101, s101, s26
	s_cmp_lt_i32 s13, 1
	s_cselect_b32 s100, s101, s100
	v_ashrrev_i32_e32 v101, 3, v175
	v_add_u32_e32 v101, s100, v101
	v_mul_u32_u24_e32 v101, 0x1200, v101
	v_add_u32_e32 v101, v101, v100
	s_lshl_b32 s101, s18, 7
	v_add_u32_e32 v101, s101, v101
	global_load_dwordx4 v[54:57], v101, s[92:93] offset:1024
	v_add_u32_e32 v101, 0x24000, v101
	global_load_dwordx4 v[58:61], v101, s[92:93] offset:1024
	v_ashrrev_i32_e32 v101, 2, v175
	s_lshl_b32 s101, s18, 6
	v_add_u32_e32 v101, s101, v101
	v_mul_u32_u24_e32 v101, 0x9000, v101
	s_lshl_b32 s101, s100, 1
	v_add_u32_e32 v101, s101, v101
	v_lshlrev_b32_e32 v102, 1, v175
	v_and_b32_e32 v102, 6, v102
	v_lshl_add_u32 v101, v102, 4, v101
	v_readlane_b32 s100, v250, 10
	v_readlane_b32 s101, v250, 11
	s_nop 4
	global_load_dwordx4 v[62:65], v101, s[100:101] offset:16
	global_load_dwordx4 v[66:69], v101, s[100:101]
	v_or_b32_e32 v4, s4, v0
	v_ashrrev_i32_e32 v5, 31, v4
	v_lshlrev_b64 v[4:5], 2, v[4:5]
	v_lshl_add_u64 v[4:5], s[94:95], 0, v[4:5]
	global_load_dword v74, v[4:5], off
	v_lshlrev_b32_e32 v102, 2, v2
	v_readlane_b32 s4, v253, 0
	v_readlane_b32 s60, v251, 50
	v_readlane_b32 s61, v251, 51
	v_cmp_gt_i32_e64 s[100:101], 64, v2
	v_lshl_add_u32 v103, s4, 2, v102
	s_mov_b64 s[6:7], exec
	s_and_b64 exec, exec, s[100:101]
	s_nop 1
	global_load_dword v138, v103, s[60:61]
	s_mov_b64 exec, s[6:7]
	s_and_b64 vcc, exec, s[0:1]
	s_cbranch_vccz .Latt_pro_wait
	v_readlane_b32 s8, v253, 6
	v_readlane_b32 s9, v253, 7
	s_mul_i32 s3, s18, 0x744
	s_nop 1
	s_add_u32 s8, s8, s3
	s_addc_u32 s9, s9, 0
	s_movk_i32 s26, 0x1d1
	v_cmp_gt_i32_e64 s[100:101], s26, v2
	s_and_b64 exec, exec, s[100:101]
	global_load_dword v136, v102, s[8:9]
	s_movk_i32 s26, 0xd1
	v_cmp_gt_i32_e64 s[100:101], s26, v2
	s_and_b64 exec, exec, s[100:101]
	global_load_dword v137, v102, s[8:9] offset:1024
	s_mov_b64 exec, s[6:7]
.Latt_pro_wait:
	v_readlane_b32 s3, v252, 0
	s_waitcnt vmcnt(0)
	v_cmp_gt_i32_e64 s[100:101], 64, v2
	s_and_b64 exec, exec, s[100:101]
	ds_write_b32 v102, v138 offset:42832
	s_mov_b64 exec, s[6:7]
	s_and_b64 vcc, exec, s[0:1]
	s_cbranch_vccz .Latt_pro_done
	v_add_u32_e32 v103, s3, v102
	v_fma_f32 v136, v136, s20, -v74
	v_fma_f32 v137, v137, s20, -v74
	s_movk_i32 s26, 0x1d1
	v_cmp_gt_i32_e64 s[100:101], s26, v2
	s_and_b64 exec, exec, s[100:101]
	ds_write_b32 v103, v136
	s_movk_i32 s26, 0xd1
	v_cmp_gt_i32_e64 s[100:101], s26, v2
	s_and_b64 exec, exec, s[100:101]
	ds_write_b32 v103, v137 offset:1024
	s_mov_b64 exec, s[6:7]
.Latt_pro_done:
	v_readlane_b32 s56, v251, 46
	v_readlane_b32 s57, v251, 47
	v_readlane_b32 s58, v251, 48
	v_readlane_b32 s59, v251, 49
	v_readlane_b32 s60, v251, 50
	v_readlane_b32 s61, v251, 51
	v_readlane_b32 s62, v251, 52
	v_readlane_b32 s63, v251, 53
	v_readlane_b32 s64, v251, 54
	v_readlane_b32 s65, v251, 55
	v_readlane_b32 s66, v251, 56
	v_readlane_b32 s67, v251, 57
	v_readlane_b32 s68, v251, 58
	v_readlane_b32 s69, v251, 59
	v_readlane_b32 s70, v251, 60
	v_readlane_b32 s71, v251, 61

.Lmod_loop:
	v_lshlrev_b32_e32 v0, 3, v175
	v_and_b32_e32 v34, 0x1f8, v0
	v_lshlrev_b32_e32 v0, 2, v34
	s_add_i32 s6, s22, s13
	s_ashr_i32 s7, s6, 31
	s_add_i32 s10, s6, 1
	s_ashr_i32 s11, s10, 31
	s_ashr_i32 s12, s6, 11
	s_cmpk_gt_i32 s6, 0x3fff
	s_cselect_b32 s8, 8, s12
	s_mov_b32 s9, 0
	s_ashr_i32 s12, s10, 11
	s_cmpk_gt_i32 s10, 0x3fff
	s_cselect_b32 s0, 8, s12
	s_mov_b32 s1, 0
	s_waitcnt vmcnt(0)
	v_mov_b32_e32 v14, v176
	v_mov_b32_e32 v15, v177
	v_mov_b32_e32 v16, v178
	v_mov_b32_e32 v17, v179
	v_mov_b32_e32 v10, v180
	v_mov_b32_e32 v11, v181
	v_mov_b32_e32 v12, v182
	v_mov_b32_e32 v13, v183
	v_mov_b32_e32 v6, v184
	v_mov_b32_e32 v7, v185
	v_mov_b32_e32 v8, v186
	v_mov_b32_e32 v9, v187
	v_mov_b32_e32 v2, v188
	v_mov_b32_e32 v3, v189
	v_mov_b32_e32 v4, v190
	v_mov_b32_e32 v5, v191
	v_mov_b32_e32 v30, v192
	v_mov_b32_e32 v31, v193
	v_mov_b32_e32 v32, v194
	v_mov_b32_e32 v33, v195
	v_mov_b32_e32 v26, v196
	v_mov_b32_e32 v27, v197
	v_mov_b32_e32 v28, v198
	v_mov_b32_e32 v29, v199
	v_mov_b32_e32 v22, v200
	v_mov_b32_e32 v23, v201
	v_mov_b32_e32 v24, v202
	v_mov_b32_e32 v25, v203
	v_mov_b32_e32 v18, v208
	v_mov_b32_e32 v19, v209
	v_mov_b32_e32 v20, v210
	v_mov_b32_e32 v21, v211
	s_add_u32 s2, s8, s17
	s_addc_u32 s3, s9, s16
	s_mul_hi_u32 s8, s2, 0x3000
	s_mulk_i32 s3, 0x3000
	s_mulk_i32 s2, 0x3000
	s_add_i32 s3, s8, s3
	s_add_u32 s8, s28, s2
	s_addc_u32 s9, s29, s3
	s_lshl_b64 s[2:3], s[6:7], 11
	s_add_u32 s6, s96, s2
	s_addc_u32 s7, s97, s3
	s_add_u32 s0, s0, s17
	s_addc_u32 s2, s1, s16
	s_mul_hi_u32 s3, s0, 0x3000
	s_mulk_i32 s2, 0x3000
	s_mul_i32 s12, s0, 0x3000
	s_lshl_b64 s[0:1], s[10:11], 11
	s_add_i32 s3, s3, s2
	s_add_u32 s0, s96, s0
	s_addc_u32 s1, s97, s1
	s_add_u32 s2, s28, s12
	v_and_b32_e32 v35, 64, v207
	s_addc_u32 s3, s29, s3
	s_add_u32 s10, s8, 0x1000
	s_addc_u32 s11, s9, 0
	v_or_b32_e32 v98, 0x800, v0
	global_load_dwordx4 v[36:39], v0, s[4:5] offset:16
	global_load_dwordx4 v[40:43], v0, s[4:5]
	global_load_dwordx4 v[44:47], v0, s[4:5] offset:2064
	global_load_dwordx4 v[48:51], v0, s[4:5] offset:2048
	global_load_dwordx4 v[52:55], v0, s[10:11] offset:16
	global_load_dwordx4 v[56:59], v0, s[10:11]
	global_load_dwordx4 v[60:63], v98, s[10:11] offset:16
	global_load_dwordx4 v[64:67], v98, s[10:11]
	global_load_dwordx4 v[68:71], v0, s[8:9] offset:16
	global_load_dwordx4 v[72:75], v0, s[8:9]
	global_load_dwordx4 v[76:79], v0, s[8:9] offset:2064
	global_load_dwordx4 v[80:83], v0, s[8:9] offset:2048
	s_add_i32 s26, s23, 64
	s_cmpk_gt_i32 s26, 0xdf
	s_cselect_b32 s26, 0, 0x200
	s_add_i32 s26, s26, s22
	s_add_i32 s26, s26, s13
	s_cmpk_gt_i32 s26, 0x3fff
	s_cselect_b32 s14, s19, s21
	s_cselect_b32 s15, s18, s20
	s_cselect_b32 s100, 0x4000, 0
	s_sub_i32 s100, s26, s100
	s_lshr_b32 s101, s100, 20
	s_lshl_b32 s100, s100, 12
	s_add_u32 s14, s14, s100
	s_addc_u32 s15, s15, s101
	global_load_dwordx4 v[176:179], v0, s[14:15]
	global_load_dwordx4 v[180:183], v0, s[14:15] offset:16
	global_load_dwordx4 v[184:187], v0, s[14:15] offset:2048
	global_load_dwordx4 v[188:191], v0, s[14:15] offset:2064
	s_add_i32 s26, s26, 1
	s_cmpk_gt_i32 s26, 0x3fff
	s_cselect_b32 s14, s19, s21
	s_cselect_b32 s15, s18, s20
	s_cselect_b32 s100, 0x4000, 0
	s_sub_i32 s100, s26, s100
	s_lshr_b32 s101, s100, 20
	s_lshl_b32 s100, s100, 12
	s_add_u32 s14, s14, s100
	s_addc_u32 s15, s15, s101
	global_load_dwordx4 v[192:195], v0, s[14:15]
	global_load_dwordx4 v[196:199], v0, s[14:15] offset:16
	global_load_dwordx4 v[200:203], v0, s[14:15] offset:2048
	global_load_dwordx4 v[208:211], v0, s[14:15] offset:2064
	v_mov_b32_e32 v124, v15
	v_mov_b32_e32 v125, v11
	v_mov_b32_e32 v128, v7
	v_mov_b32_e32 v129, v3
	v_xor_b32_e32 v134, 1, v207
	v_add_u32_e32 v35, 64, v35
	v_mov_b32_e32 v122, v14
	v_mov_b32_e32 v123, v10
	v_mov_b32_e32 v126, v6
	v_mov_b32_e32 v127, v2
	v_xor_b32_e32 v135, 2, v207
	v_pk_mul_f32 v[124:125], v[124:125], v[124:125]
	v_pk_mul_f32 v[128:129], v[128:129], v[128:129]
	v_cmp_lt_i32_e32 vcc, v134, v35
	v_mov_b32_e32 v130, v16
	v_mov_b32_e32 v131, v12
	v_mov_b32_e32 v140, v8
	v_mov_b32_e32 v141, v4
	v_pk_fma_f32 v[132:133], v[122:123], v[122:123], v[124:125]
	v_pk_fma_f32 v[144:145], v[126:127], v[126:127], v[128:129]
	v_cndmask_b32_e32 v148, v207, v134, vcc
	v_cmp_lt_i32_e32 vcc, v135, v35
	v_mov_b32_e32 v138, v17
	v_mov_b32_e32 v139, v13
	v_mov_b32_e32 v142, v9
	v_mov_b32_e32 v143, v5
	v_cndmask_b32_e32 v149, v207, v135, vcc
	v_pk_fma_f32 v[146:147], v[130:131], v[130:131], v[132:133]
	v_pk_fma_f32 v[140:141], v[140:141], v[140:141], v[144:145]
	v_lshlrev_b32_e32 v99, 2, v148
	v_lshlrev_b32_e32 v100, 2, v149
	v_pk_fma_f32 v[84:85], v[138:139], v[138:139], v[146:147]
	v_pk_fma_f32 v[86:87], v[142:143], v[142:143], v[140:141]
	s_mov_b32 s8, 0x3a800000
	s_mov_b32 s10, 0x800000
	v_mov_b32_e32 v94, v23
	v_mov_b32_e32 v95, v19
	v_mov_b32_e32 v92, v22
	v_mov_b32_e32 v93, v18
	v_pk_mul_f32 v[94:95], v[94:95], v[94:95]
	v_mov_b32_e32 v88, v24
	v_mov_b32_e32 v89, v20
	v_pk_fma_f32 v[92:93], v[92:93], v[92:93], v[94:95]
	v_mov_b32_e32 v96, v31
	v_mov_b32_e32 v97, v27
	v_mov_b32_e32 v90, v25
	v_mov_b32_e32 v91, v21
	v_pk_fma_f32 v[88:89], v[88:89], v[88:89], v[92:93]
	v_mov_b32_e32 v94, v30
	v_mov_b32_e32 v95, v26
	v_pk_mul_f32 v[96:97], v[96:97], v[96:97]
	v_pk_fma_f32 v[88:89], v[90:91], v[90:91], v[88:89]
	v_mov_b32_e32 v90, v32
	v_mov_b32_e32 v91, v28
	v_pk_fma_f32 v[94:95], v[94:95], v[94:95], v[96:97]
	v_mov_b32_e32 v92, v33
	v_mov_b32_e32 v93, v29
	v_pk_fma_f32 v[90:91], v[90:91], v[90:91], v[94:95]
	s_waitcnt vmcnt(15)
	v_pk_add_f32 v[52:53], v[52:53], 1.0 op_sel_hi:[1,0]
	v_pk_fma_f32 v[90:91], v[92:93], v[92:93], v[90:91]
	v_mov_b32_e32 v93, v84
	v_mov_b32_e32 v92, v90
	v_mov_b32_e32 v84, v91
	v_pk_add_f32 v[84:85], v[92:93], v[84:85]
	v_mov_b32_e32 v90, v88
	v_mov_b32_e32 v91, v86
	v_pk_add_f32 v[84:85], v[84:85], v[90:91]
	v_mov_b32_e32 v86, v89
	v_pk_add_f32 v[84:85], v[84:85], v[86:87]
	s_nop 1
	v_add_f32_dpp v84, v84, v84 quad_perm:[1,0,3,2] row_mask:0xf bank_mask:0xf
	v_add_f32_dpp v85, v85, v85 quad_perm:[1,0,3,2] row_mask:0xf bank_mask:0xf
	v_xor_b32_e32 v88, 4, v207
	v_cmp_lt_i32_e32 vcc, v88, v35
	v_xor_b32_e32 v89, 8, v207
	s_waitcnt vmcnt(14)
	v_pk_add_f32 v[56:57], v[56:57], 1.0 op_sel_hi:[1,0]
	s_waitcnt lgkmcnt(0)
	s_nop 0
	s_nop 1
	v_add_f32_dpp v84, v84, v84 quad_perm:[2,3,0,1] row_mask:0xf bank_mask:0xf
	v_add_f32_dpp v85, v85, v85 quad_perm:[2,3,0,1] row_mask:0xf bank_mask:0xf
	v_cndmask_b32_e32 v88, v207, v88, vcc
	v_lshlrev_b32_e32 v88, 2, v88
	v_cmp_lt_i32_e32 vcc, v89, v35
	v_pk_add_f32 v[58:59], v[58:59], 1.0 op_sel_hi:[1,0]
	s_waitcnt lgkmcnt(0)
	s_nop 0
	s_nop 1
	v_add_f32_dpp v84, v84, v84 row_half_mirror row_mask:0xf bank_mask:0xf
	v_add_f32_dpp v85, v85, v85 row_half_mirror row_mask:0xf bank_mask:0xf
	v_cndmask_b32_e32 v89, v207, v89, vcc
	v_lshlrev_b32_e32 v89, 2, v89
	v_xor_b32_e32 v88, 16, v207
	v_cmp_lt_i32_e32 vcc, v88, v35
	s_waitcnt lgkmcnt(0)
	s_nop 0
	s_nop 1
	v_add_f32_dpp v84, v84, v84 row_mirror row_mask:0xf bank_mask:0xf
	v_add_f32_dpp v85, v85, v85 row_mirror row_mask:0xf bank_mask:0xf
	v_cndmask_b32_e32 v88, v207, v88, vcc
	v_lshlrev_b32_e32 v88, 2, v88
	v_xor_b32_e32 v89, 32, v207
	v_cmp_lt_i32_e32 vcc, v89, v35
	s_waitcnt lgkmcnt(0)
	s_nop 0
	v_mov_b32_e32 v86, v84
	v_mov_b32_e32 v87, v85
	s_nop 1
	v_permlane16_swap_b32 v86, v84
	v_permlane16_swap_b32 v87, v85
	s_nop 0
	v_cndmask_b32_e32 v35, v207, v89, vcc
	v_lshlrev_b32_e32 v35, 2, v35
	v_pk_add_f32 v[54:55], v[54:55], 1.0 op_sel_hi:[1,0]
	s_waitcnt vmcnt(12)
	v_pk_add_f32 v[64:65], v[64:65], 1.0 op_sel_hi:[1,0]
	s_waitcnt lgkmcnt(0)
	v_pk_add_f32 v[84:85], v[84:85], v[86:87]
	v_mov_b32_e32 v86, v84
	v_mov_b32_e32 v87, v85
	s_nop 1
	v_permlane32_swap_b32 v86, v84
	v_permlane32_swap_b32 v87, v85
	s_nop 0
	v_pk_add_f32 v[66:67], v[66:67], 1.0 op_sel_hi:[1,0]
	v_pk_add_f32 v[60:61], v[60:61], 1.0 op_sel_hi:[1,0]
	v_pk_add_f32 v[62:63], v[62:63], 1.0 op_sel_hi:[1,0]
	s_waitcnt lgkmcnt(0)
	v_pk_add_f32 v[84:85], v[84:85], v[86:87]
	s_nop 0
	v_pk_fma_f32 v[84:85], v[84:85], s[8:9], v[240:241] op_sel_hi:[1,0,0]
	s_add_u32 s8, s2, 0x1000
	v_mul_f32_e32 v35, 0x4b800000, v85
	v_cmp_gt_f32_e32 vcc, s10, v85
	s_addc_u32 s9, s3, 0
	s_add_i32 s23, s23, 64
	v_cndmask_b32_e32 v35, v85, v35, vcc
	v_rsq_f32_e32 v35, v35
	v_lshlrev_b32_e32 v85, 1, v34
	s_addk_i32 s22, 0x200
	s_cmpk_gt_i32 s23, 0xdf
	v_mul_f32_e32 v34, 0x45800000, v35
	v_cndmask_b32_e32 v34, v35, v34, vcc
	v_pk_mul_f32 v[14:15], v[14:15], v[34:35] op_sel_hi:[1,0]
	v_pk_mul_f32 v[16:17], v[16:17], v[34:35] op_sel_hi:[1,0]
	v_pk_mul_f32 v[10:11], v[10:11], v[34:35] op_sel_hi:[1,0]
	v_pk_mul_f32 v[12:13], v[12:13], v[34:35] op_sel_hi:[1,0]
	v_pk_mul_f32 v[14:15], v[40:41], v[14:15]
	v_pk_mul_f32 v[16:17], v[42:43], v[16:17]
	v_pk_mul_f32 v[10:11], v[10:11], v[36:37]
	v_pk_mul_f32 v[12:13], v[12:13], v[38:39]
	v_pk_mul_f32 v[6:7], v[6:7], v[34:35] op_sel_hi:[1,0]
	v_pk_mul_f32 v[8:9], v[8:9], v[34:35] op_sel_hi:[1,0]
	v_pk_mul_f32 v[2:3], v[2:3], v[34:35] op_sel_hi:[1,0]
	v_pk_mul_f32 v[4:5], v[4:5], v[34:35] op_sel_hi:[1,0]
	s_waitcnt vmcnt(10)
	v_pk_fma_f32 v[14:15], v[56:57], v[14:15], v[72:73]
	v_pk_fma_f32 v[16:17], v[58:59], v[16:17], v[74:75]
	v_pk_fma_f32 v[10:11], v[10:11], v[52:53], v[68:69]
	v_pk_fma_f32 v[12:13], v[12:13], v[54:55], v[70:71]
	v_pk_mul_f32 v[6:7], v[6:7], v[48:49]
	v_pk_mul_f32 v[8:9], v[8:9], v[50:51]
	v_pk_mul_f32 v[2:3], v[2:3], v[44:45]
	v_pk_mul_f32 v[4:5], v[4:5], v[46:47]
	v_cvt_pk_bf16_f32 v14, v14, v15
	v_cvt_pk_bf16_f32 v15, v16, v17
	v_cvt_pk_bf16_f32 v16, v10, v11
	v_cvt_pk_bf16_f32 v17, v12, v13
	s_waitcnt vmcnt(8)
	v_pk_fma_f32 v[6:7], v[6:7], v[64:65], v[80:81]
	v_pk_fma_f32 v[8:9], v[8:9], v[66:67], v[82:83]
	v_pk_fma_f32 v[2:3], v[2:3], v[60:61], v[76:77]
	v_pk_fma_f32 v[4:5], v[4:5], v[62:63], v[78:79]
	v_cvt_pk_bf16_f32 v6, v6, v7
	v_cvt_pk_bf16_f32 v7, v8, v9
	v_cvt_pk_bf16_f32 v8, v2, v3
	v_cvt_pk_bf16_f32 v9, v4, v5
	global_store_dwordx4 v85, v[14:17], s[6:7]
	global_store_dwordx4 v85, v[6:9], s[6:7] offset:1024
	v_mul_f32_e32 v0, 0x4b800000, v84
	v_cmp_gt_f32_e32 vcc, s10, v84
	v_cndmask_b32_e32 v0, v84, v0, vcc
	v_rsq_f32_e32 v0, v0
	v_mul_f32_e32 v86, 0x45800000, v0
	v_cndmask_b32_e32 v0, v0, v86, vcc
	v_pk_mul_f32 v[30:31], v[30:31], v[0:1] op_sel_hi:[1,0]
	v_pk_mul_f32 v[30:31], v[40:41], v[30:31]
	v_pk_fma_f32 v[30:31], v[56:57], v[30:31], v[72:73]
	v_pk_mul_f32 v[32:33], v[32:33], v[0:1] op_sel_hi:[1,0]
	v_pk_mul_f32 v[32:33], v[42:43], v[32:33]
	v_pk_fma_f32 v[32:33], v[58:59], v[32:33], v[74:75]
	v_pk_mul_f32 v[26:27], v[26:27], v[0:1] op_sel_hi:[1,0]
	v_pk_mul_f32 v[26:27], v[36:37], v[26:27]
	v_pk_fma_f32 v[26:27], v[52:53], v[26:27], v[68:69]
	v_pk_mul_f32 v[28:29], v[28:29], v[0:1] op_sel_hi:[1,0]
	v_pk_mul_f32 v[28:29], v[38:39], v[28:29]
	v_pk_fma_f32 v[28:29], v[54:55], v[28:29], v[70:71]
	v_cvt_pk_bf16_f32 v2, v30, v31
	v_cvt_pk_bf16_f32 v3, v32, v33
	v_cvt_pk_bf16_f32 v4, v26, v27
	v_cvt_pk_bf16_f32 v5, v28, v29
	global_store_dwordx4 v85, v[2:5], s[0:1]
	v_pk_mul_f32 v[22:23], v[22:23], v[0:1] op_sel_hi:[1,0]
	v_pk_mul_f32 v[22:23], v[48:49], v[22:23]
	v_pk_fma_f32 v[22:23], v[64:65], v[22:23], v[80:81]
	v_pk_mul_f32 v[24:25], v[24:25], v[0:1] op_sel_hi:[1,0]
	v_pk_mul_f32 v[24:25], v[50:51], v[24:25]
	v_pk_fma_f32 v[24:25], v[66:67], v[24:25], v[82:83]
	v_pk_mul_f32 v[18:19], v[18:19], v[0:1] op_sel_hi:[1,0]
	v_pk_mul_f32 v[18:19], v[44:45], v[18:19]
	v_pk_fma_f32 v[18:19], v[60:61], v[18:19], v[76:77]
	v_pk_mul_f32 v[20:21], v[20:21], v[0:1] op_sel_hi:[1,0]
	v_pk_mul_f32 v[20:21], v[46:47], v[20:21]
	v_pk_fma_f32 v[20:21], v[62:63], v[20:21], v[78:79]
	v_cvt_pk_bf16_f32 v6, v22, v23
	v_cvt_pk_bf16_f32 v7, v24, v25
	v_cvt_pk_bf16_f32 v8, v18, v19
	v_cvt_pk_bf16_f32 v9, v20, v21
	global_store_dwordx4 v85, v[6:9], s[0:1] offset:1024
	s_cbranch_scc1 .LBB0_760
	s_branch .Lmod_loop
